# ph0 context K/V cache conversion: 16 loads per thread in flight instead of a load-wait chain
# baseline (speedup 1.0000x reference)
.LBB0_1125:
	s_nop 0
	v_lshl_add_u32 v0, s56, 9, v192
	s_mov_b32 s0, 0x100000
	v_cmp_gt_i32_e32 vcc, s0, v0
	s_and_saveexec_b64 s[22:23], vcc
	s_cbranch_execz .LBB0_1128
	s_lshl_b32 s36, s24, 9
	v_lshlrev_b32_e32 v1, 6, v192
	v_readlane_b32 s0, v253, 12
	v_lshl_add_u32 v6, s56, 15, v1
	v_ashrrev_i32_e32 v1, 31, v0
	s_ashr_i32 s37, s36, 31
	v_readlane_b32 s1, v253, 13
	s_lshl_b32 s3, s24, 15
	v_lshl_add_u64 v[2:3], v[0:1], 2, s[8:9]
	s_lshl_b64 s[38:39], s[36:37], 2
	v_lshl_add_u64 v[4:5], v[0:1], 1, s[0:1]
	s_lshl_b64 s[40:41], s[36:37], 1
	s_mov_b64 s[42:43], 0
	s_cmpk_lg_u32 s24, 0x100
	s_cbranch_scc1 .LBB0_1127
	v_ashrrev_i32_e32 v8, 14, v0
	v_ashrrev_i32_e32 v9, 31, v8
	v_and_b32_e32 v7, 0x3fc0, v6
	v_lshlrev_b64 v[8:9], 16, v[8:9]
	v_lshrrev_b32_e32 v10, 6, v0
	v_lshlrev_b32_e32 v178, 2, v7
	v_lshl_add_u64 v[8:9], s[10:11], 0, v[8:9]
	v_lshl_add_u64 v[8:9], v[8:9], 0, v[178:179]
	v_and_b32_e32 v178, 0xfc, v10
	v_lshl_add_u64 v[8:9], v[8:9], 0, v[178:179]
	global_load_dword v16, v[2:3], off
	global_load_dword v24, v[8:9], off
	v_lshl_add_u64 v[2:3], v[2:3], 0, s[38:39]
	v_lshl_add_u64 v[8:9], v[8:9], 0, s[38:39]
	global_load_dword v17, v[2:3], off
	global_load_dword v25, v[8:9], off
	v_lshl_add_u64 v[2:3], v[2:3], 0, s[38:39]
	v_lshl_add_u64 v[8:9], v[8:9], 0, s[38:39]
	global_load_dword v18, v[2:3], off
	global_load_dword v26, v[8:9], off
	v_lshl_add_u64 v[2:3], v[2:3], 0, s[38:39]
	v_lshl_add_u64 v[8:9], v[8:9], 0, s[38:39]
	global_load_dword v19, v[2:3], off
	global_load_dword v27, v[8:9], off
	v_lshl_add_u64 v[2:3], v[2:3], 0, s[38:39]
	v_lshl_add_u64 v[8:9], v[8:9], 0, s[38:39]
	global_load_dword v20, v[2:3], off
	global_load_dword v28, v[8:9], off
	v_lshl_add_u64 v[2:3], v[2:3], 0, s[38:39]
	v_lshl_add_u64 v[8:9], v[8:9], 0, s[38:39]
	global_load_dword v21, v[2:3], off
	global_load_dword v29, v[8:9], off
	v_lshl_add_u64 v[2:3], v[2:3], 0, s[38:39]
	v_lshl_add_u64 v[8:9], v[8:9], 0, s[38:39]
	global_load_dword v22, v[2:3], off
	global_load_dword v30, v[8:9], off
	v_lshl_add_u64 v[2:3], v[2:3], 0, s[38:39]
	v_lshl_add_u64 v[8:9], v[8:9], 0, s[38:39]
	global_load_dword v23, v[2:3], off
	global_load_dword v31, v[8:9], off
	v_add_co_u32_e32 v10, vcc, 0x200000, v4
	s_nop 1
	v_addc_co_u32_e32 v11, vcc, 0, v5, vcc
	s_waitcnt vmcnt(14)
	v_cvt_pk_bf16_f32 v1, v16, v179
	v_cvt_pk_bf16_f32 v12, v24, v179
	global_store_short v[4:5], v1, off
	global_store_short v[10:11], v12, off
	v_lshl_add_u64 v[4:5], v[4:5], 0, s[40:41]
	v_lshl_add_u64 v[10:11], v[10:11], 0, s[40:41]
	s_waitcnt vmcnt(14)
	v_cvt_pk_bf16_f32 v13, v17, v179
	v_cvt_pk_bf16_f32 v14, v25, v179
	global_store_short v[4:5], v13, off
	global_store_short v[10:11], v14, off
	v_lshl_add_u64 v[4:5], v[4:5], 0, s[40:41]
	v_lshl_add_u64 v[10:11], v[10:11], 0, s[40:41]
	s_waitcnt vmcnt(14)
	v_cvt_pk_bf16_f32 v1, v18, v179
	v_cvt_pk_bf16_f32 v12, v26, v179
	global_store_short v[4:5], v1, off
	global_store_short v[10:11], v12, off
	v_lshl_add_u64 v[4:5], v[4:5], 0, s[40:41]
	v_lshl_add_u64 v[10:11], v[10:11], 0, s[40:41]
	s_waitcnt vmcnt(14)
	v_cvt_pk_bf16_f32 v13, v19, v179
	v_cvt_pk_bf16_f32 v14, v27, v179
	global_store_short v[4:5], v13, off
	global_store_short v[10:11], v14, off
	v_lshl_add_u64 v[4:5], v[4:5], 0, s[40:41]
	v_lshl_add_u64 v[10:11], v[10:11], 0, s[40:41]
	s_waitcnt vmcnt(14)
	v_cvt_pk_bf16_f32 v1, v20, v179
	v_cvt_pk_bf16_f32 v12, v28, v179
	global_store_short v[4:5], v1, off
	global_store_short v[10:11], v12, off
	v_lshl_add_u64 v[4:5], v[4:5], 0, s[40:41]
	v_lshl_add_u64 v[10:11], v[10:11], 0, s[40:41]
	s_waitcnt vmcnt(14)
	v_cvt_pk_bf16_f32 v13, v21, v179
	v_cvt_pk_bf16_f32 v14, v29, v179
	global_store_short v[4:5], v13, off
	global_store_short v[10:11], v14, off
	v_lshl_add_u64 v[4:5], v[4:5], 0, s[40:41]
	v_lshl_add_u64 v[10:11], v[10:11], 0, s[40:41]
	s_waitcnt vmcnt(14)
	v_cvt_pk_bf16_f32 v1, v22, v179
	v_cvt_pk_bf16_f32 v12, v30, v179
	global_store_short v[4:5], v1, off
	global_store_short v[10:11], v12, off
	v_lshl_add_u64 v[4:5], v[4:5], 0, s[40:41]
	v_lshl_add_u64 v[10:11], v[10:11], 0, s[40:41]
	s_waitcnt vmcnt(14)
	v_cvt_pk_bf16_f32 v13, v23, v179
	v_cvt_pk_bf16_f32 v14, v31, v179
	global_store_short v[4:5], v13, off
	global_store_short v[10:11], v14, off
	s_branch .LBB0_1128
